# adds: split-K sample-tile store_partials (P7 and P10) with ping-pong gate loads and counted waits; stream-last sample unit gate loads hoisted; q/k/v staging both trips in flight
# speedup vs baseline: 1.0220x; 1.0220x over previous
; __device__ __forceinline__ float bf2f(bf16_t h) { return __uint_as_float((unsigned)h << 16); }
; __device__ __forceinline__ void mlstm_sample_unit(const Frame& F, int b, int h) {
;     ...
;     for (int i = tid; i < 1024; i += 512) { const int t = i >> 8, d = i & 255; const bf16_t* row = P + (size_t)(SP + b * 4 + t) * NIN;
;         sq[i] = bf2f(row[C_MQ + h * 256 + d]) * 0.0625f; sk[i] = bf2f(row[C_MK + h * 256 + d]); sv[i] = bf2f(row[C_MV + h * 256 + d]); }
;     ...
;         const int pair = tid >> 5, sub = tid & 31, t = pair >> 2, s = pair & 3; float a = 0.f, c = 0.f;
; #pragma unroll
;         for (int e = 0; e < 8; ++e) { const int d = sub * 8 + e; a += sq[t * 256 + d] * sk[s * 256 + d]; if (s == 0) c += sq[t * 256 + d] * F.in[5][(size_t)bh * 256 + d]; }
.LBB0_351:
	s_movk_i32 s35, 0x2c00
	v_mad_i64_i32 v[10:11], s[46:47], v6, s35, v[96:97]
	v_lshl_add_u64 v[12:13], v[10:11], 0, v[0:1]
	v_lshl_add_u64 v[14:15], v[10:11], 0, v[2:3]
	v_lshl_add_u64 v[10:11], v[10:11], 0, v[4:5]
	global_load_ushort v9, v[12:13], off offset:3072
	global_load_ushort v12, v[14:15], off
	global_load_ushort v10, v[10:11], off
	v_add_u32_e32 v6, 2, v6
	v_mad_i64_i32 v[16:17], s[46:47], v6, s35, v[96:97]
	v_lshl_add_u64 v[18:19], v[16:17], 0, v[0:1]
	v_lshl_add_u64 v[20:21], v[16:17], 0, v[2:3]
	v_lshl_add_u64 v[16:17], v[16:17], 0, v[4:5]
	global_load_ushort v22, v[18:19], off offset:3072
	global_load_ushort v23, v[20:21], off
	global_load_ushort v24, v[16:17], off
	v_add_u32_e32 v6, 2, v6
	s_waitcnt vmcnt(3)
	v_lshlrev_b32_e32 v9, 16, v9
	v_lshlrev_b32_e32 v11, 16, v12
	v_lshlrev_b32_e32 v10, 16, v10
	v_mul_f32_e32 v9, 0x3d800000, v9
	ds_write_b32 v7, v10 offset:8192
	ds_write2st64_b32 v7, v9, v11 offset1:16
	v_add_u32_e32 v7, 0x800, v7
	s_waitcnt vmcnt(0)
	v_lshlrev_b32_e32 v22, 16, v22
	v_lshlrev_b32_e32 v23, 16, v23
	v_lshlrev_b32_e32 v24, 16, v24
	v_mul_f32_e32 v22, 0x3d800000, v22
	ds_write_b32 v7, v24 offset:8192
	ds_write2st64_b32 v7, v22, v23 offset1:16
	v_add_u32_e32 v7, 0x800, v7
	s_or_b64 exec, exec, s[42:43]
	s_and_saveexec_b64 s[42:43], s[70:71]
	ds_write_b32 v113, v1 offset:12288
	s_or_b64 exec, exec, s[42:43]
	s_waitcnt lgkmcnt(0)
	s_barrier
	ds_read_b32 v0, v115
	ds_read_b32 v2, v117 offset:4096
	s_ashr_i32 s35, s34, 31
	v_readlane_b32 s12, v245, 37
	s_lshl_b64 s[64:65], s[34:35], 10
	v_readlane_b32 s22, v245, 47
	v_readlane_b32 s23, v245, 48
	s_add_u32 s46, s22, s64
	s_addc_u32 s47, s23, s65
	v_mov_b32_e32 v3, 0
	v_lshlrev_b32_e32 v4, 2, v82
	v_readlane_b32 s13, v245, 38
	v_readlane_b32 s14, v245, 39
	v_readlane_b32 s15, v245, 40
	v_readlane_b32 s16, v245, 41
	v_readlane_b32 s17, v245, 42
	v_readlane_b32 s18, v245, 43
	v_readlane_b32 s19, v245, 44
	v_readlane_b32 s20, v245, 45
	v_readlane_b32 s21, v245, 46
	v_readlane_b32 s24, v245, 49
	v_readlane_b32 s25, v245, 50
	v_readlane_b32 s26, v245, 51
	v_readlane_b32 s27, v245, 52
	s_and_saveexec_b64 s[42:43], s[2:3]
	global_load_dwordx4 v[20:23], v4, s[46:47]
	global_load_dwordx4 v[24:27], v4, s[46:47] offset:16
	s_or_b64 exec, exec, s[42:43]
	ds_read_b32 v5, v115 offset:4
	ds_read_b32 v6, v117 offset:4100
	ds_read_b32 v7, v115 offset:8
	ds_read_b32 v8, v117 offset:4104
	ds_read_b32 v9, v115 offset:12
	ds_read_b32 v10, v117 offset:4108
	ds_read_b32 v11, v115 offset:16
	ds_read_b32 v12, v117 offset:4112
	ds_read_b32 v13, v115 offset:20
	ds_read_b32 v14, v117 offset:4116
	ds_read_b32 v15, v115 offset:24
	ds_read_b32 v16, v117 offset:4120
	ds_read_b32 v17, v115 offset:28
	ds_read_b32 v18, v117 offset:4124
	s_waitcnt lgkmcnt(0)
	s_and_saveexec_b64 s[42:43], s[2:3]
	s_waitcnt vmcnt(0)
	v_fma_f32 v3, v0, v20, 0
	v_fmac_f32_e32 v3, v5, v21
	v_fmac_f32_e32 v3, v7, v22
	v_fmac_f32_e32 v3, v9, v23
	v_fmac_f32_e32 v3, v11, v24
	v_fmac_f32_e32 v3, v13, v25
	v_fmac_f32_e32 v3, v15, v26
	v_fmac_f32_e32 v3, v17, v27
	s_or_b64 exec, exec, s[42:43]
	v_fma_f32 v0, v0, v2, 0
	v_fmac_f32_e32 v0, v5, v6
	v_fmac_f32_e32 v0, v7, v8
	v_fmac_f32_e32 v0, v9, v10
	v_fmac_f32_e32 v0, v11, v12
	v_fmac_f32_e32 v0, v13, v14
	v_fmac_f32_e32 v0, v15, v16
	v_fmac_f32_e32 v0, v17, v18
	ds_bpermute_b32 v2, v83, v3
	ds_bpermute_b32 v4, v83, v0
	s_waitcnt lgkmcnt(1)
	v_add_f32_e32 v2, v3, v2
	s_waitcnt lgkmcnt(0)
	v_add_f32_e32 v0, v0, v4
	ds_bpermute_b32 v3, v101, v2
	ds_bpermute_b32 v4, v101, v0
	s_waitcnt lgkmcnt(1)
	v_add_f32_e32 v2, v2, v3
	s_waitcnt lgkmcnt(0)
	v_add_f32_e32 v0, v0, v4
	ds_bpermute_b32 v3, v105, v2
	ds_bpermute_b32 v4, v105, v0
	s_waitcnt lgkmcnt(1)
	v_add_f32_e32 v2, v2, v3
	s_waitcnt lgkmcnt(0)
	v_add_f32_e32 v4, v0, v4
	ds_bpermute_b32 v3, v107, v2
	ds_bpermute_b32 v5, v107, v4
	s_waitcnt lgkmcnt(1)
	v_add_f32_e32 v0, v2, v3
	s_waitcnt lgkmcnt(0)
	v_add_f32_e32 v3, v4, v5
	ds_bpermute_b32 v4, v109, v3
	ds_bpermute_b32 v2, v109, v0
	s_and_saveexec_b64 s[42:43], s[74:75]
	s_cbranch_execz .LBB0_373
	s_waitcnt lgkmcnt(1)
	v_add_f32_e32 v3, v3, v4
	ds_write_b32 v119, v3 offset:12288
	s_and_b64 exec, exec, s[2:3]
	s_cbranch_execz .LBB0_373
	s_waitcnt lgkmcnt(1)
	v_add_f32_e32 v0, v0, v2
	ds_write_b32 v121, v0 offset:12352

; __device__ __forceinline__ float bf2f(bf16_t h) { return __uint_as_float((unsigned)h << 16); }
; __device__ __forceinline__ void mlstm_sample_unit(const Frame& F, int b, int h) {
;     ...
;     for (int i = tid; i < 1024; i += 512) { const int t = i >> 8, d = i & 255; const bf16_t* row = P + (size_t)(SP + b * 4 + t) * NIN;
;         sq[i] = bf2f(row[C_MQ + h * 256 + d]) * 0.0625f; sk[i] = bf2f(row[C_MK + h * 256 + d]); sv[i] = bf2f(row[C_MV + h * 256 + d]); }
;     if (tid < 64) sS[tid] = 0.f;
;     __syncthreads();
;     {
;         const int pair = tid >> 5, sub = tid & 31, t = pair >> 2, s = pair & 3; float a = 0.f, c = 0.f;
; #pragma unroll
;         for (int e = 0; e < 8; ++e) { const int d = sub * 8 + e; a += sq[t * 256 + d] * sk[s * 256 + d]; if (s == 0) c += sq[t * 256 + d] * F.in[5][(size_t)bh * 256 + d]; }
; #pragma unroll
;         for (int o = 16; o >= 1; o >>= 1) { a += __shfl_xor(a, o); c += __shfl_xor(c, o); }
;         if (sub == 0) { sS[pair] = a; if (s == 0) sS[16 + t] = c; } }
.LBB0_539:
	s_movk_i32 s35, 0x2c00
	v_mad_i64_i32 v[10:11], s[38:39], v6, s35, v[96:97]
	v_lshl_add_u64 v[12:13], v[10:11], 0, v[0:1]
	v_lshl_add_u64 v[14:15], v[10:11], 0, v[2:3]
	v_lshl_add_u64 v[10:11], v[10:11], 0, v[4:5]
	global_load_ushort v9, v[12:13], off offset:3072
	global_load_ushort v12, v[14:15], off
	global_load_ushort v10, v[10:11], off
	v_add_u32_e32 v6, 2, v6
	v_mad_i64_i32 v[16:17], s[38:39], v6, s35, v[96:97]
	v_lshl_add_u64 v[18:19], v[16:17], 0, v[0:1]
	v_lshl_add_u64 v[20:21], v[16:17], 0, v[2:3]
	v_lshl_add_u64 v[16:17], v[16:17], 0, v[4:5]
	global_load_ushort v22, v[18:19], off offset:3072
	global_load_ushort v23, v[20:21], off
	global_load_ushort v24, v[16:17], off
	v_add_u32_e32 v6, 2, v6
	s_waitcnt vmcnt(3)
	v_lshlrev_b32_e32 v9, 16, v9
	v_lshlrev_b32_e32 v11, 16, v12
	v_lshlrev_b32_e32 v10, 16, v10
	v_mul_f32_e32 v9, 0x3d800000, v9
	ds_write_b32 v7, v10 offset:8192
	ds_write2st64_b32 v7, v9, v11 offset1:16
	v_add_u32_e32 v7, 0x800, v7
	s_waitcnt vmcnt(0)
	v_lshlrev_b32_e32 v22, 16, v22
	v_lshlrev_b32_e32 v23, 16, v23
	v_lshlrev_b32_e32 v24, 16, v24
	v_mul_f32_e32 v22, 0x3d800000, v22
	ds_write_b32 v7, v24 offset:8192
	ds_write2st64_b32 v7, v22, v23 offset1:16
	v_add_u32_e32 v7, 0x800, v7
	s_or_b64 exec, exec, s[0:1]
	s_and_saveexec_b64 s[0:1], s[68:69]
	ds_write_b32 v113, v1 offset:12288
	s_or_b64 exec, exec, s[0:1]
	s_waitcnt lgkmcnt(0)
	s_barrier
	ds_read_b32 v0, v115
	ds_read_b32 v2, v117 offset:4096
	s_ashr_i32 s35, s34, 31
	v_readlane_b32 s12, v245, 37
	s_lshl_b64 s[62:63], s[34:35], 10
	v_readlane_b32 s22, v245, 47
	v_readlane_b32 s23, v245, 48
	s_add_u32 s0, s22, s62
	s_addc_u32 s1, s23, s63
	v_mov_b32_e32 v3, 0
	v_lshlrev_b32_e32 v4, 2, v82
	v_readlane_b32 s13, v245, 38
	v_readlane_b32 s14, v245, 39
	v_readlane_b32 s15, v245, 40
	v_readlane_b32 s16, v245, 41
	v_readlane_b32 s17, v245, 42
	v_readlane_b32 s18, v245, 43
	v_readlane_b32 s19, v245, 44
	v_readlane_b32 s20, v245, 45
	v_readlane_b32 s21, v245, 46
	v_readlane_b32 s24, v245, 49
	v_readlane_b32 s25, v245, 50
	v_readlane_b32 s26, v245, 51
	v_readlane_b32 s27, v245, 52
	s_and_saveexec_b64 s[38:39], s[4:5]
	global_load_dwordx4 v[20:23], v4, s[0:1]
	global_load_dwordx4 v[24:27], v4, s[0:1] offset:16
	s_or_b64 exec, exec, s[38:39]
	ds_read_b32 v5, v115 offset:4
	ds_read_b32 v6, v117 offset:4100
	ds_read_b32 v7, v115 offset:8
	ds_read_b32 v8, v117 offset:4104
	ds_read_b32 v9, v115 offset:12
	ds_read_b32 v10, v117 offset:4108
	ds_read_b32 v11, v115 offset:16
	ds_read_b32 v12, v117 offset:4112
	ds_read_b32 v13, v115 offset:20
	ds_read_b32 v14, v117 offset:4116
	ds_read_b32 v15, v115 offset:24
	ds_read_b32 v16, v117 offset:4120
	ds_read_b32 v17, v115 offset:28
	ds_read_b32 v18, v117 offset:4124
	s_waitcnt lgkmcnt(0)
	s_and_saveexec_b64 s[38:39], s[4:5]
	s_waitcnt vmcnt(0)
	v_fma_f32 v3, v0, v20, 0
	v_fmac_f32_e32 v3, v5, v21
	v_fmac_f32_e32 v3, v7, v22
	v_fmac_f32_e32 v3, v9, v23
	v_fmac_f32_e32 v3, v11, v24
	v_fmac_f32_e32 v3, v13, v25
	v_fmac_f32_e32 v3, v15, v26
	v_fmac_f32_e32 v3, v17, v27
	s_or_b64 exec, exec, s[38:39]
	v_fma_f32 v0, v0, v2, 0
	v_fmac_f32_e32 v0, v5, v6
	v_fmac_f32_e32 v0, v7, v8
	v_fmac_f32_e32 v0, v9, v10
	v_fmac_f32_e32 v0, v11, v12
	v_fmac_f32_e32 v0, v13, v14
	v_fmac_f32_e32 v0, v15, v16
	v_fmac_f32_e32 v0, v17, v18
	ds_bpermute_b32 v2, v83, v3
	ds_bpermute_b32 v4, v83, v0
	s_waitcnt lgkmcnt(1)
	v_add_f32_e32 v2, v3, v2
	s_waitcnt lgkmcnt(0)
	v_add_f32_e32 v0, v0, v4
	ds_bpermute_b32 v3, v99, v2
	ds_bpermute_b32 v4, v99, v0
	s_waitcnt lgkmcnt(1)
	v_add_f32_e32 v2, v2, v3
	s_waitcnt lgkmcnt(0)
	v_add_f32_e32 v0, v0, v4
	ds_bpermute_b32 v3, v105, v2
	ds_bpermute_b32 v4, v105, v0
	s_waitcnt lgkmcnt(1)
	v_add_f32_e32 v2, v2, v3
	s_waitcnt lgkmcnt(0)
	v_add_f32_e32 v4, v0, v4
	ds_bpermute_b32 v3, v107, v2
	ds_bpermute_b32 v5, v107, v4
	s_waitcnt lgkmcnt(1)
	v_add_f32_e32 v0, v2, v3
	s_waitcnt lgkmcnt(0)
	v_add_f32_e32 v3, v4, v5
	ds_bpermute_b32 v4, v109, v3
	ds_bpermute_b32 v2, v109, v0
	s_and_saveexec_b64 s[0:1], s[6:7]
	s_cbranch_execz .LBB0_561
	s_waitcnt lgkmcnt(1)
	v_add_f32_e32 v3, v3, v4
	ds_write_b32 v119, v3 offset:12288
	s_and_b64 exec, exec, s[4:5]
	s_cbranch_execz .LBB0_561
	s_waitcnt lgkmcnt(1)
	v_add_f32_e32 v0, v0, v2
	ds_write_b32 v121, v0 offset:12352
; __device__ __forceinline__ float logsigmoid_fast(float x) { return fminf(x, 0.f) - __logf(1.f + __expf(-fabsf(x))); }
; __device__ __forceinline__ void mlstm_sample_unit(const Frame& F, int b, int h) {
;     ...
;     const float m0 = F.in[6][bh];
;     { float acc = 0.f;
; #pragma unroll
;       for (int t = 0; t < 4; ++t) { const float* gp = gates + (size_t)(SP + b * 4 + t) * 8; li[t] = gp[h] + F.in[15][h]; acc += logsigmoid_fast(gp[4 + h] + F.in[16][h]); bcum[t] = acc; } }
; #pragma unroll
;     for (int t = 0; t < 4; ++t) { const float mi = bcum[t] + m0; float m = mi;
; #pragma unroll
;         for (int s = 0; s < 4; ++s) if (s <= t) m = fmaxf(m, bcum[t] - bcum[s] + li[s]);
;         mt[t] = m; at[t] = __expf(mi - m); float dsum = at[t] * sS[16 + t];
; #pragma unroll
;         for (int s = 0; s < 4; ++s) { sm[t][s] = (s <= t) ? sS[t * 4 + s] * __expf(bcum[t] - bcum[s] + li[s] - m) : 0.f; dsum += sm[t][s]; }
;         den[t] = fmaxf(fabsf(dsum), __expf(-m)); }
;     const float mnew = mt[3], decay = __expf(bcum[3] + m0 - mnew);
; #pragma unroll
;     for (int s = 0; s < 4; ++s) gs[s] = __expf(bcum[3] - bcum[s] + li[s] - mnew);
.LBB0_561:
	s_or_b64 exec, exec, s[0:1]
	v_readlane_b32 s12, v245, 37
	s_add_i32 s54, s28, 0x2000
	s_lshl_b64 s[64:65], s[34:35], 2
	v_readlane_b32 s24, v245, 49
	v_readlane_b32 s25, v245, 50
	s_add_u32 s0, s24, s64
	s_addc_u32 s1, s25, s65
	s_waitcnt lgkmcnt(0)
	s_barrier
	global_load_dword v0, v1, s[0:1]
	s_lshl_b32 s0, s29, 2
	v_readlane_b32 s13, v245, 38
	v_readlane_b32 s14, v245, 39
	v_readlane_b32 s15, v245, 40
	v_readlane_b32 s16, v245, 41
	v_readlane_b32 s17, v245, 42
	v_readlane_b32 s18, v245, 43
	v_readlane_b32 s19, v245, 44
	v_readlane_b32 s20, v245, 45
	v_readlane_b32 s21, v245, 46
	v_readlane_b32 s22, v245, 47
	v_readlane_b32 s23, v245, 48
	v_readlane_b32 s26, v245, 51
	v_readlane_b32 s27, v245, 52
	s_add_u32 s29, s91, s0
	s_addc_u32 s42, s92, 0
	v_readlane_b32 s12, v245, 3
	s_ashr_i32 s55, s54, 31
	v_mov_b32_e32 v2, s0
	v_readlane_b32 s13, v245, 4
	v_readlane_b32 s14, v245, 5
	v_readlane_b32 s15, v245, 6
	v_readlane_b32 s16, v245, 7
	v_readlane_b32 s17, v245, 8
	v_readlane_b32 s18, v245, 9
	v_readlane_b32 s19, v245, 10
	v_readlane_b32 s20, v245, 11
	v_readlane_b32 s21, v245, 12
	v_readlane_b32 s22, v245, 13
	v_readlane_b32 s23, v245, 14
	v_readlane_b32 s24, v245, 15
	v_readlane_b32 s25, v245, 16
	v_readlane_b32 s26, v245, 17
	v_readlane_b32 s27, v245, 18
	s_lshl_b64 s[0:1], s[54:55], 5
	s_add_u32 s0, s29, s0
	s_addc_u32 s1, s42, s1
	global_load_dword v3, v1, s[0:1] offset:16
	v_add_u32_e32 v155, 0x2000, v85
	global_load_dword v4, v2, s[26:27]
	v_readlane_b32 s12, v245, 21
	v_readlane_b32 s13, v245, 22
	v_add_u32_e32 v154, 0x2400, v85
	v_add_u32_e32 v147, 0x2800, v85
	v_add_u32_e32 v95, 0x2c00, v85
	v_readlane_b32 s14, v245, 23
	v_readlane_b32 s15, v245, 24
	global_load_dword v5, v2, s[12:13]
	v_readlane_b32 s12, v245, 1
	global_load_dword v2, v1, s[0:1]
	global_load_dword v70, v1, s[0:1] offset:32
	global_load_dword v71, v1, s[0:1] offset:48
	global_load_dword v72, v1, s[0:1] offset:64
	global_load_dword v73, v1, s[0:1] offset:80
	global_load_dword v74, v1, s[0:1] offset:96
	global_load_dword v75, v1, s[0:1] offset:112
	v_readlane_b32 s13, v245, 2
	v_readlane_b32 s16, v245, 25
	v_readlane_b32 s17, v245, 26
	v_readlane_b32 s18, v245, 27
	v_readlane_b32 s19, v245, 28
	v_readlane_b32 s20, v245, 29
	v_readlane_b32 s21, v245, 30
	v_readlane_b32 s22, v245, 31
	v_readlane_b32 s23, v245, 32
	v_readlane_b32 s24, v245, 33
	v_readlane_b32 s25, v245, 34
	v_readlane_b32 s26, v245, 35
	v_readlane_b32 s27, v245, 36
	s_waitcnt vmcnt(1)
	v_add_f32_e32 v3, v5, v3
	v_min_f32_e32 v6, 0, v3
	v_mul_f32_e64 v3, |v3|, s77
	v_exp_f32_e32 v3, v3
	s_waitcnt vmcnt(0)
	v_add_f32_e32 v2, v4, v2
	v_add_f32_e32 v3, 1.0, v3
	v_cmp_gt_f32_e32 vcc, s82, v3
	s_and_b64 s[0:1], vcc, exec
	s_cselect_b32 s0, 32, 0
	v_ldexp_f32 v3, v3, s0
	v_log_f32_e32 v3, v3
	s_add_i32 s38, s28, 0x2001
	s_ashr_i32 s39, s38, 31
	v_mul_f32_e32 v7, 0x3f317217, v3
	v_fma_f32 v7, v3, s83, -v7
	v_fmac_f32_e32 v7, 0x3377d1cf, v3
	v_fmac_f32_e32 v7, 0x3f317217, v3
	v_cmp_lt_f32_e64 s[0:1], |v3|, s90
	s_nop 1
	v_cndmask_b32_e64 v3, v3, v7, s[0:1]
	s_lshl_b64 s[0:1], s[38:39], 5
	v_cndmask_b32_e32 v7, 0, v133, vcc
	s_add_u32 s0, s29, s0
	v_sub_f32_e32 v3, v3, v7
	s_addc_u32 s1, s42, s1
	v_sub_f32_e32 v3, v6, v3
	v_mov_b32_e32 v6, v70
	v_add_f32_e32 v3, 0, v3
	s_waitcnt vmcnt(0)
	v_add_f32_e32 v20, v4, v6
	v_mov_b32_e32 v6, v71
	s_waitcnt vmcnt(0)
	v_add_f32_e32 v6, v5, v6
	v_min_f32_e32 v7, 0, v6
	v_mul_f32_e64 v6, |v6|, s77
	v_exp_f32_e32 v6, v6
	s_nop 0
	v_add_f32_e32 v6, 1.0, v6
	v_cmp_gt_f32_e32 vcc, s82, v6
	s_and_b64 s[0:1], vcc, exec
	s_cselect_b32 s0, 32, 0
	v_ldexp_f32 v6, v6, s0
	v_log_f32_e32 v6, v6
	s_add_i32 s46, s28, 0x2002
	s_ashr_i32 s47, s46, 31
	v_mul_f32_e32 v8, 0x3f317217, v6
	v_fma_f32 v8, v6, s83, -v8
	v_fmac_f32_e32 v8, 0x3377d1cf, v6
	v_fmac_f32_e32 v8, 0x3f317217, v6
	v_cmp_lt_f32_e64 s[0:1], |v6|, s90
	s_nop 1
	v_cndmask_b32_e64 v6, v6, v8, s[0:1]
	v_cndmask_b32_e32 v8, 0, v133, vcc
	s_lshl_b64 s[0:1], s[46:47], 5
	v_sub_f32_e32 v6, v6, v8
	s_add_u32 s0, s29, s0
	v_sub_f32_e32 v6, v7, v6
	s_addc_u32 s1, s42, s1
	v_add_f32_e32 v21, v3, v6
	v_mov_b32_e32 v6, v72
	s_waitcnt vmcnt(0)
	v_add_f32_e32 v22, v4, v6
	v_mov_b32_e32 v6, v73
	s_waitcnt vmcnt(0)
	v_add_f32_e32 v6, v5, v6
	v_min_f32_e32 v7, 0, v6
	v_mul_f32_e64 v6, |v6|, s77
	v_exp_f32_e32 v6, v6
	s_nop 0
	v_add_f32_e32 v6, 1.0, v6
	v_cmp_gt_f32_e32 vcc, s82, v6
	s_and_b64 s[0:1], vcc, exec
	s_cselect_b32 s0, 32, 0
	v_ldexp_f32 v6, v6, s0
	v_log_f32_e32 v6, v6
	s_add_i32 s60, s28, 0x2003
	s_ashr_i32 s61, s60, 31
	v_mul_f32_e32 v8, 0x3f317217, v6
	v_fma_f32 v8, v6, s83, -v8
	v_fmac_f32_e32 v8, 0x3377d1cf, v6
	v_fmac_f32_e32 v8, 0x3f317217, v6
	v_cmp_lt_f32_e64 s[0:1], |v6|, s90
	s_nop 1
	v_cndmask_b32_e64 v6, v6, v8, s[0:1]
	v_cndmask_b32_e32 v8, 0, v133, vcc
	s_lshl_b64 s[0:1], s[60:61], 5
	v_sub_f32_e32 v6, v6, v8
	s_add_u32 s0, s29, s0
	v_sub_f32_e32 v6, v7, v6
	s_addc_u32 s1, s42, s1
	v_add_f32_e32 v23, v21, v6
	v_mov_b32_e32 v6, v74
	s_waitcnt vmcnt(0)
	v_add_f32_e32 v4, v4, v6
	v_mov_b32_e32 v6, v75
	s_waitcnt vmcnt(0)
	v_add_f32_e32 v5, v5, v6
	v_min_f32_e32 v6, 0, v5
	v_mul_f32_e64 v5, |v5|, s77
	v_exp_f32_e32 v5, v5
	s_nop 0
	v_add_f32_e32 v5, 1.0, v5
	v_cmp_gt_f32_e32 vcc, s82, v5
	s_and_b64 s[0:1], vcc, exec
	s_cselect_b32 s0, 32, 0
	v_ldexp_f32 v5, v5, s0
	v_log_f32_e32 v5, v5
	s_nop 0
	v_mul_f32_e32 v7, 0x3f317217, v5
	v_fma_f32 v7, v5, s83, -v7
	v_fmac_f32_e32 v7, 0x3377d1cf, v5
	v_fmac_f32_e32 v7, 0x3f317217, v5
	v_cmp_lt_f32_e64 s[0:1], |v5|, s90
	s_nop 1
	v_cndmask_b32_e64 v5, v5, v7, s[0:1]
	v_cndmask_b32_e32 v7, 0, v133, vcc
	v_sub_f32_e32 v5, v5, v7
	v_sub_f32_e32 v5, v6, v5
	v_add_f32_e32 v5, v23, v5
	v_sub_f32_e32 v7, v5, v3
	v_sub_f32_e32 v8, v5, v21
	v_add_f32_e32 v6, v0, v5
	v_add_f32_e32 v7, v2, v7
	v_add_f32_e32 v8, v20, v8
	v_sub_f32_e32 v10, v5, v23
	v_sub_f32_e32 v5, v5, v5
	v_max3_f32 v9, v6, v7, v8
	v_add_f32_e32 v10, v22, v10
	v_add_f32_e32 v4, v4, v5
	v_max3_f32 v145, v9, v10, v4
	v_sub_f32_e32 v4, v4, v145
	v_mul_f32_e32 v4, 0x3fb8aa3b, v4
	v_exp_f32_e32 v101, v4
	v_sub_f32_e32 v4, v7, v145
	v_mul_f32_e32 v4, 0x3fb8aa3b, v4
	v_exp_f32_e32 v102, v4
	v_sub_f32_e32 v4, v8, v145
	v_mul_f32_e32 v4, 0x3fb8aa3b, v4
	v_sub_f32_e32 v5, v6, v145
	v_exp_f32_e32 v103, v4
	v_sub_f32_e32 v4, v10, v145
	v_mul_f32_e32 v5, 0x3fb8aa3b, v5
	v_mul_f32_e32 v4, 0x3fb8aa3b, v4
	v_exp_f32_e32 v98, v5
	v_exp_f32_e32 v100, v4
	ds_read2_b32 v[4:5], v155 offset1:8
	ds_read2_b32 v[6:7], v154 offset1:8
	ds_read2_b32 v[8:9], v147 offset1:8
	ds_read2_b32 v[16:17], v95 offset1:8
	ds_read2_b32 v[10:11], v155 offset0:16 offset1:24
	ds_read2_b32 v[12:13], v154 offset0:16 offset1:24
	ds_read2_b32 v[14:15], v147 offset0:16 offset1:24
	ds_read2_b32 v[18:19], v95 offset0:16 offset1:24
	s_and_saveexec_b64 s[0:1], s[12:13]
	s_cbranch_execz .LBB0_563
; __device__ __forceinline__ void mlstm_sample_unit(const Frame& F, int b, int h) {
;     ...
;     for (int t = 0; t < 4; ++t) { const float mi = bcum[t] + m0; float m = mi;
; #pragma unroll
;         for (int s = 0; s < 4; ++s) if (s <= t) m = fmaxf(m, bcum[t] - bcum[s] + li[s]);
;         mt[t] = m; at[t] = __expf(mi - m); float dsum = at[t] * sS[16 + t];
; #pragma unroll
;         for (int s = 0; s < 4; ++s) { sm[t][s] = (s <= t) ? sS[t * 4 + s] * __expf(bcum[t] - bcum[s] + li[s] - m) : 0.f; dsum += sm[t][s]; }
;         den[t] = fmaxf(fabsf(dsum), __expf(-m)); }
;     const float mnew = mt[3], decay = __expf(bcum[3] + m0 - mnew);
; #pragma unroll
;     for (int s = 0; s < 4; ++s) gs[s] = __expf(bcum[3] - bcum[s] + li[s] - mnew);
;     const int r8 = lane >> 3, seg = lane & 7, w = F.wave;
;     const float* c0b = F.in[4] + (size_t)bh * 65536 + (size_t)(w * 32 + r8) * 256 + seg * 4;
;     float* c1b = F.out + O_CS + (size_t)bh * 65536 + (size_t)(w * 32 + r8) * 256 + seg * 4;
;     float acc[4][4], gv[4][4];
; #pragma unroll
;     for (int rg = 0; rg < 4; ++rg)
; #pragma unroll
;         for (int t = 0; t < 4; ++t) { acc[rg][t] = 0.f; gv[rg][t] = gs[t] * sv[t * 256 + w * 32 + rg * 8 + r8]; }
;     if (tid == 0) {
; #pragma unroll
;         for (int t = 0; t < 4; ++t) { sS[40 + t] = at[t]; sS[44 + t] = den[t];
; #pragma unroll
;             for (int s2 = 0; s2 < 4; ++s2) sS[48 + t * 4 + s2] = sm[t][s2]; } }
	v_add_f32_e32 v24, v0, v23
	v_sub_f32_e32 v25, v23, v3
	v_sub_f32_e32 v27, v23, v21
	v_add_f32_e32 v38, v0, v21
	v_sub_f32_e32 v39, v21, v3
	v_sub_f32_e32 v21, v21, v21
	v_add_f32_e32 v0, v0, v3
	v_sub_f32_e32 v3, v3, v3
	v_add_f32_e32 v25, v2, v25
	v_add_f32_e32 v27, v20, v27
	v_sub_f32_e32 v23, v23, v23
	v_add_f32_e32 v39, v2, v39
	v_add_f32_e32 v20, v20, v21
	v_add_f32_e32 v2, v2, v3
	v_max_f32_e32 v26, v24, v25
	v_add_f32_e32 v23, v22, v23
	v_max3_f32 v44, v38, v39, v20
	v_max_f32_e32 v3, v0, v2
	v_max3_f32 v35, v26, v27, v23
	v_sub_f32_e32 v20, v20, v44
	v_sub_f32_e32 v0, v0, v3
	v_sub_f32_e32 v22, v24, v35
	v_sub_f32_e32 v24, v25, v35
	v_mul_f32_e32 v20, 0x3fb8aa3b, v20
	v_mul_f32_e32 v0, 0x3fb8aa3b, v0
	v_mul_f32_e32 v24, 0x3fb8aa3b, v24
	v_sub_f32_e32 v21, v38, v44
	v_sub_f32_e32 v38, v39, v44
	v_exp_f32_e32 v39, v20
	v_exp_f32_e32 v20, v0
	v_sub_f32_e32 v0, v2, v3
	v_exp_f32_e32 v32, v24
	v_sub_f32_e32 v24, v27, v35
	v_mul_f32_e32 v0, 0x3fb8aa3b, v0
	v_mul_f32_e32 v24, 0x3fb8aa3b, v24
	v_exp_f32_e32 v0, v0
	ds_read_b32 v43, v1 offset:12288
	ds_read_b64 v[36:37], v1 offset:12304
	ds_read_b96 v[40:42], v1 offset:12320
	v_exp_f32_e32 v33, v24
	ds_read_b128 v[24:27], v1 offset:12352
	ds_read_b128 v[28:31], v1 offset:12336
	v_mul_f32_e32 v2, 0xbfb8aa3b, v3
	v_mul_f32_e32 v38, 0x3fb8aa3b, v38
	v_exp_f32_e32 v2, v2
	v_mul_f32_e32 v21, 0x3fb8aa3b, v21
	v_exp_f32_e32 v38, v38
	v_exp_f32_e32 v21, v21
	s_waitcnt lgkmcnt(4)
	v_mul_f32_e32 v0, v0, v43
	v_mul_f32_e32 v22, 0x3fb8aa3b, v22
	v_mul_f32_e32 v44, 0xbfb8aa3b, v44
	s_waitcnt lgkmcnt(1)
	v_fma_f32 v3, v20, v24, v0
	v_exp_f32_e32 v22, v22
	v_sub_f32_e32 v23, v23, v35
	v_exp_f32_e32 v44, v44
	v_max_f32_e64 v24, |v3|, v2
	v_mul_f32_e32 v2, 0xbfb8aa3b, v145
	v_mul_f32_e32 v23, 0x3fb8aa3b, v23
	v_exp_f32_e32 v43, v2
	v_mov_b32_e32 v2, v1
	v_mov_b32_e32 v3, v1
	v_pk_mul_f32 v[36:37], v[38:39], v[36:37]
	v_exp_f32_e32 v23, v23
	ds_write_b128 v1, v[0:3] offset:12480
	v_fma_f32 v0, v21, v25, v36
	v_mul_f32_e32 v35, 0xbfb8aa3b, v35
	v_add_f32_e32 v0, v0, v37
	v_pk_mul_f32 v[32:33], v[32:33], v[40:41]
	v_exp_f32_e32 v35, v35
	v_max_f32_e64 v25, |v0|, v44
	v_fma_f32 v0, v22, v26, v32
	v_add_f32_e32 v0, v0, v33
	v_mul_f32_e32 v34, v23, v42
	v_fmac_f32_e32 v0, v23, v42
	v_mov_b32_e32 v23, v98
	ds_write_b128 v1, v[20:23] offset:12448
	s_waitcnt lgkmcnt(2)
	v_pk_mul_f32 v[20:21], v[102:103], v[28:29]
	v_max_f32_e64 v26, |v0|, v35
	v_fma_f32 v0, v98, v27, v20
	v_add_f32_e32 v0, v0, v21
	v_pk_mul_f32 v[22:23], v[100:101], v[30:31]
	v_mov_b32_e32 v38, v1
	v_add_f32_e32 v0, v0, v22
	v_add_f32_e32 v0, v23, v0
	v_mov_b32_e32 v39, v1
	v_mov_b32_e32 v35, v1
	v_max_f32_e64 v27, |v0|, v43
	ds_write_b128 v1, v[36:39] offset:12496
	ds_write_b128 v1, v[32:35] offset:12512
	ds_write_b128 v1, v[24:27] offset:12464
	ds_write_b128 v1, v[20:23] offset:12528

; __device__ __forceinline__ void store_partials(const f32x4 (&acc)[2][2][4][2], const Unit& u, int row0, int col0, const float* gate, float* part) {
;     int poff = (u.kz * MS + (row0 - SP)) * D + col0; asm volatile("" : "+v"(poff));
; #pragma unroll
;     for (int am = 0; am < 4; ++am) { f32x4 gv[2][2][2];
; #pragma unroll
;         for (int m2 = 0; m2 < 2; ++m2) { const int rr = row0 - SP + (am >> 1) * HALF + ((am & 1) * 2 + m2) * 16; const int go = (rr >> 2) * NMOD + col0;
; #pragma unroll
;             for (int bj = 0; bj < 2; ++bj)
; #pragma unroll
;                 for (int n = 0; n < 2; ++n) gv[m2][bj][n] = *(const f32x4*)(gate + (go + bj * HALF + n * 16)); }
; #pragma unroll
;         for (int m2 = 0; m2 < 2; ++m2) { const int po = poff + ((am >> 1) * HALF + ((am & 1) * 2 + m2) * 16) * D;
; #pragma unroll
;             for (int bj = 0; bj < 2; ++bj)
; #pragma unroll
;                 for (int n = 0; n < 2; ++n) *(f32x4*)(part + (po + bj * HALF + n * 16)) = gv[m2][bj][n] * acc[am >> 1][bj][(am & 1) * 2 + m2][n]; } }
.LBB0_887:
	s_lshl_b32 s19, s28, 20
	v_add_u32_e32 v165, 0xffffe000, v168
	v_lshlrev_b32_e32 v165, 11, v165
	v_add3_u32 v164, v162, s19, v165
	v_add_u32_e32 v165, 0xffffe000, v168
	v_lshrrev_b32_e32 v165, 2, v165
	v_mad_u32_u24 v188, v165, s55, v162
	v_ashrrev_i32_e32 v189, 31, v188
	v_lshl_add_u64 v[188:189], v[188:189], 2, s[8:9]
	global_load_dwordx4 v[128:131], v[188:189], off
	global_load_dwordx4 v[132:135], v[188:189], off offset:64
	global_load_dwordx4 v[136:139], v[188:189], off offset:512
	global_load_dwordx4 v[140:143], v[188:189], off offset:576
	v_add_u32_e32 v165, 0xffffe010, v168
	v_lshrrev_b32_e32 v165, 2, v165
	v_mad_u32_u24 v188, v165, s55, v162
	v_ashrrev_i32_e32 v189, 31, v188
	v_lshl_add_u64 v[188:189], v[188:189], 2, s[8:9]
	global_load_dwordx4 v[172:175], v[188:189], off
	global_load_dwordx4 v[176:179], v[188:189], off offset:64
	global_load_dwordx4 v[180:183], v[188:189], off offset:512
	global_load_dwordx4 v[184:187], v[188:189], off offset:576
	v_ashrrev_i32_e32 v165, 31, v164
	v_lshl_add_u64 v[190:191], v[164:165], 2, s[10:11]
	s_waitcnt vmcnt(4)
	v_pk_mul_f32 v[124:125], v[124:125], v[128:129]
	v_pk_mul_f32 v[126:127], v[126:127], v[130:131]
	global_store_dwordx4 v[190:191], v[124:127], off
	v_pk_mul_f32 v[120:121], v[120:121], v[132:133]
	v_pk_mul_f32 v[122:123], v[122:123], v[134:135]
	global_store_dwordx4 v[190:191], v[120:123], off offset:64
	v_pk_mul_f32 v[108:109], v[108:109], v[136:137]
	v_pk_mul_f32 v[110:111], v[110:111], v[138:139]
	global_store_dwordx4 v[190:191], v[108:111], off offset:512
	v_pk_mul_f32 v[104:105], v[104:105], v[140:141]
	v_pk_mul_f32 v[106:107], v[106:107], v[142:143]
	global_store_dwordx4 v[190:191], v[104:107], off offset:576
	v_add_u32_e32 v165, 0xffffe020, v168
	v_lshrrev_b32_e32 v165, 2, v165
	v_mad_u32_u24 v188, v165, s55, v162
	v_ashrrev_i32_e32 v189, 31, v188
	v_lshl_add_u64 v[188:189], v[188:189], 2, s[8:9]
	global_load_dwordx4 v[128:131], v[188:189], off
	global_load_dwordx4 v[132:135], v[188:189], off offset:64
	global_load_dwordx4 v[136:139], v[188:189], off offset:512
	global_load_dwordx4 v[140:143], v[188:189], off offset:576
	s_waitcnt vmcnt(8)
	v_add_co_u32_e32 v192, vcc, 0x20000, v190
	s_nop 1
	v_addc_co_u32_e32 v193, vcc, 0, v191, vcc
	v_pk_mul_f32 v[116:117], v[116:117], v[172:173]
	v_pk_mul_f32 v[118:119], v[118:119], v[174:175]
	global_store_dwordx4 v[192:193], v[116:119], off
	v_pk_mul_f32 v[112:113], v[112:113], v[176:177]
	v_pk_mul_f32 v[114:115], v[114:115], v[178:179]
	global_store_dwordx4 v[192:193], v[112:115], off offset:64
	v_pk_mul_f32 v[100:101], v[100:101], v[180:181]
	v_pk_mul_f32 v[102:103], v[102:103], v[182:183]
	global_store_dwordx4 v[192:193], v[100:103], off offset:512
	v_pk_mul_f32 v[96:97], v[96:97], v[184:185]
	v_pk_mul_f32 v[98:99], v[98:99], v[186:187]
	global_store_dwordx4 v[192:193], v[96:99], off offset:576
	v_add_u32_e32 v165, 0xffffe030, v168
	v_lshrrev_b32_e32 v165, 2, v165
	v_mad_u32_u24 v188, v165, s55, v162
	v_ashrrev_i32_e32 v189, 31, v188
	v_lshl_add_u64 v[188:189], v[188:189], 2, s[8:9]
	global_load_dwordx4 v[172:175], v[188:189], off
	global_load_dwordx4 v[176:179], v[188:189], off offset:64
	global_load_dwordx4 v[180:183], v[188:189], off offset:512
	global_load_dwordx4 v[184:187], v[188:189], off offset:576
	s_waitcnt vmcnt(8)
	v_add_co_u32_e32 v192, vcc, 0x40000, v190
	s_nop 1
	v_addc_co_u32_e32 v193, vcc, 0, v191, vcc
	v_pk_mul_f32 v[92:93], v[92:93], v[128:129]
	v_pk_mul_f32 v[94:95], v[94:95], v[130:131]
	global_store_dwordx4 v[192:193], v[92:95], off
	v_pk_mul_f32 v[88:89], v[88:89], v[132:133]
	v_pk_mul_f32 v[90:91], v[90:91], v[134:135]
	global_store_dwordx4 v[192:193], v[88:91], off offset:64
	v_pk_mul_f32 v[76:77], v[76:77], v[136:137]
	v_pk_mul_f32 v[78:79], v[78:79], v[138:139]
	global_store_dwordx4 v[192:193], v[76:79], off offset:512
	v_pk_mul_f32 v[72:73], v[72:73], v[140:141]
	v_pk_mul_f32 v[74:75], v[74:75], v[142:143]
	global_store_dwordx4 v[192:193], v[72:75], off offset:576
	v_add_u32_e32 v165, 0xffffe080, v168
	v_lshrrev_b32_e32 v165, 2, v165
	v_mad_u32_u24 v188, v165, s55, v162
	v_ashrrev_i32_e32 v189, 31, v188
	v_lshl_add_u64 v[188:189], v[188:189], 2, s[8:9]
	global_load_dwordx4 v[128:131], v[188:189], off
	global_load_dwordx4 v[132:135], v[188:189], off offset:64
	global_load_dwordx4 v[136:139], v[188:189], off offset:512
	global_load_dwordx4 v[140:143], v[188:189], off offset:576
	s_waitcnt vmcnt(8)
; __device__ __forceinline__ void store_partials(const f32x4 (&acc)[2][2][4][2], const Unit& u, int row0, int col0, const float* gate, float* part) {
;     ...
;     for (int am = 0; am < 4; ++am) { f32x4 gv[2][2][2];
; #pragma unroll
;         for (int m2 = 0; m2 < 2; ++m2) { const int rr = row0 - SP + (am >> 1) * HALF + ((am & 1) * 2 + m2) * 16; const int go = (rr >> 2) * NMOD + col0;
; #pragma unroll
;             for (int bj = 0; bj < 2; ++bj)
; #pragma unroll
;                 for (int n = 0; n < 2; ++n) gv[m2][bj][n] = *(const f32x4*)(gate + (go + bj * HALF + n * 16)); }
; #pragma unroll
;         for (int m2 = 0; m2 < 2; ++m2) { const int po = poff + ((am >> 1) * HALF + ((am & 1) * 2 + m2) * 16) * D;
; #pragma unroll
;             for (int bj = 0; bj < 2; ++bj)
; #pragma unroll
;                 for (int n = 0; n < 2; ++n) *(f32x4*)(part + (po + bj * HALF + n * 16)) = gv[m2][bj][n] * acc[am >> 1][bj][(am & 1) * 2 + m2][n]; } }
	v_add_co_u32_e32 v192, vcc, 0x60000, v190
	s_nop 1
	v_addc_co_u32_e32 v193, vcc, 0, v191, vcc
	v_pk_mul_f32 v[84:85], v[84:85], v[172:173]
	v_pk_mul_f32 v[86:87], v[86:87], v[174:175]
	global_store_dwordx4 v[192:193], v[84:87], off
	v_pk_mul_f32 v[80:81], v[80:81], v[176:177]
	v_pk_mul_f32 v[82:83], v[82:83], v[178:179]
	global_store_dwordx4 v[192:193], v[80:83], off offset:64
	v_pk_mul_f32 v[68:69], v[68:69], v[180:181]
	v_pk_mul_f32 v[70:71], v[70:71], v[182:183]
	global_store_dwordx4 v[192:193], v[68:71], off offset:512
	v_pk_mul_f32 v[64:65], v[64:65], v[184:185]
	v_pk_mul_f32 v[66:67], v[66:67], v[186:187]
	global_store_dwordx4 v[192:193], v[64:67], off offset:576
	v_add_u32_e32 v165, 0xffffe090, v168
	v_lshrrev_b32_e32 v165, 2, v165
	v_mad_u32_u24 v188, v165, s55, v162
	v_ashrrev_i32_e32 v189, 31, v188
	v_lshl_add_u64 v[188:189], v[188:189], 2, s[8:9]
	global_load_dwordx4 v[172:175], v[188:189], off
	global_load_dwordx4 v[176:179], v[188:189], off offset:64
	global_load_dwordx4 v[180:183], v[188:189], off offset:512
	global_load_dwordx4 v[184:187], v[188:189], off offset:576
	s_waitcnt vmcnt(8)
	v_add_co_u32_e32 v192, vcc, 0x100000, v190
	s_nop 1
	v_addc_co_u32_e32 v193, vcc, 0, v191, vcc
	v_pk_mul_f32 v[60:61], v[60:61], v[128:129]
	v_pk_mul_f32 v[62:63], v[62:63], v[130:131]
	global_store_dwordx4 v[192:193], v[60:63], off
	v_pk_mul_f32 v[56:57], v[56:57], v[132:133]
	v_pk_mul_f32 v[58:59], v[58:59], v[134:135]
	global_store_dwordx4 v[192:193], v[56:59], off offset:64
	v_pk_mul_f32 v[44:45], v[44:45], v[136:137]
	v_pk_mul_f32 v[46:47], v[46:47], v[138:139]
	global_store_dwordx4 v[192:193], v[44:47], off offset:512
	v_pk_mul_f32 v[40:41], v[40:41], v[140:141]
	v_pk_mul_f32 v[42:43], v[42:43], v[142:143]
	global_store_dwordx4 v[192:193], v[40:43], off offset:576
	v_add_u32_e32 v165, 0xffffe0a0, v168
	v_lshrrev_b32_e32 v165, 2, v165
	v_mad_u32_u24 v188, v165, s55, v162
	v_ashrrev_i32_e32 v189, 31, v188
	v_lshl_add_u64 v[188:189], v[188:189], 2, s[8:9]
	global_load_dwordx4 v[128:131], v[188:189], off
	global_load_dwordx4 v[132:135], v[188:189], off offset:64
	global_load_dwordx4 v[136:139], v[188:189], off offset:512
	global_load_dwordx4 v[140:143], v[188:189], off offset:576
	s_waitcnt vmcnt(8)
	v_add_co_u32_e32 v192, vcc, 0x120000, v190
	s_nop 1
	v_addc_co_u32_e32 v193, vcc, 0, v191, vcc
	v_pk_mul_f32 v[52:53], v[52:53], v[172:173]
	v_pk_mul_f32 v[54:55], v[54:55], v[174:175]
	global_store_dwordx4 v[192:193], v[52:55], off
	v_pk_mul_f32 v[48:49], v[48:49], v[176:177]
	v_pk_mul_f32 v[50:51], v[50:51], v[178:179]
	global_store_dwordx4 v[192:193], v[48:51], off offset:64
	v_pk_mul_f32 v[36:37], v[36:37], v[180:181]
	v_pk_mul_f32 v[38:39], v[38:39], v[182:183]
	global_store_dwordx4 v[192:193], v[36:39], off offset:512
	v_pk_mul_f32 v[32:33], v[32:33], v[184:185]
	v_pk_mul_f32 v[34:35], v[34:35], v[186:187]
	global_store_dwordx4 v[192:193], v[32:35], off offset:576
	v_add_u32_e32 v165, 0xffffe0b0, v168
	v_lshrrev_b32_e32 v165, 2, v165
	v_mad_u32_u24 v188, v165, s55, v162
	v_ashrrev_i32_e32 v189, 31, v188
	v_lshl_add_u64 v[188:189], v[188:189], 2, s[8:9]
	global_load_dwordx4 v[172:175], v[188:189], off
	global_load_dwordx4 v[176:179], v[188:189], off offset:64
	global_load_dwordx4 v[180:183], v[188:189], off offset:512
	global_load_dwordx4 v[184:187], v[188:189], off offset:576
	s_waitcnt vmcnt(8)
	v_add_co_u32_e32 v192, vcc, 0x140000, v190
	s_nop 1
	v_addc_co_u32_e32 v193, vcc, 0, v191, vcc
	v_pk_mul_f32 v[28:29], v[28:29], v[128:129]
	v_pk_mul_f32 v[30:31], v[30:31], v[130:131]
	global_store_dwordx4 v[192:193], v[28:31], off
	v_pk_mul_f32 v[24:25], v[24:25], v[132:133]
	v_pk_mul_f32 v[26:27], v[26:27], v[134:135]
	global_store_dwordx4 v[192:193], v[24:27], off offset:64
	v_pk_mul_f32 v[12:13], v[12:13], v[136:137]
	v_pk_mul_f32 v[14:15], v[14:15], v[138:139]
	global_store_dwordx4 v[192:193], v[12:15], off offset:512
	v_pk_mul_f32 v[8:9], v[8:9], v[140:141]
	v_pk_mul_f32 v[10:11], v[10:11], v[142:143]
	global_store_dwordx4 v[192:193], v[8:11], off offset:576
	s_waitcnt vmcnt(4)
	v_add_co_u32_e32 v192, vcc, 0x160000, v190
	s_nop 1
	v_addc_co_u32_e32 v193, vcc, 0, v191, vcc
	v_pk_mul_f32 v[20:21], v[20:21], v[172:173]
	v_pk_mul_f32 v[22:23], v[22:23], v[174:175]
	global_store_dwordx4 v[192:193], v[20:23], off
	v_pk_mul_f32 v[16:17], v[16:17], v[176:177]
	v_pk_mul_f32 v[18:19], v[18:19], v[178:179]
	global_store_dwordx4 v[192:193], v[16:19], off offset:64
	v_pk_mul_f32 v[4:5], v[4:5], v[180:181]
	v_pk_mul_f32 v[6:7], v[6:7], v[182:183]
	global_store_dwordx4 v[192:193], v[4:7], off offset:512
	v_pk_mul_f32 v[0:1], v[0:1], v[184:185]
	v_pk_mul_f32 v[2:3], v[2:3], v[186:187]
	global_store_dwordx4 v[192:193], v[0:3], off offset:576
	s_and_b64 vcc, exec, s[0:1]
	s_mov_b64 s[0:1], -1
	s_cbranch_vccnz .LBB0_869

; __device__ __forceinline__ void store_partials(const f32x4 (&acc)[2][2][4][2], const Unit& u, int row0, int col0, const float* gate, float* part) {
;     int poff = (u.kz * MS + (row0 - SP)) * D + col0; asm volatile("" : "+v"(poff));
; #pragma unroll
;     for (int am = 0; am < 4; ++am) { f32x4 gv[2][2][2];
; #pragma unroll
;         for (int m2 = 0; m2 < 2; ++m2) { const int rr = row0 - SP + (am >> 1) * HALF + ((am & 1) * 2 + m2) * 16; const int go = (rr >> 2) * NMOD + col0;
; #pragma unroll
;             for (int bj = 0; bj < 2; ++bj)
; #pragma unroll
;                 for (int n = 0; n < 2; ++n) gv[m2][bj][n] = *(const f32x4*)(gate + (go + bj * HALF + n * 16)); }
; #pragma unroll
;         for (int m2 = 0; m2 < 2; ++m2) { const int po = poff + ((am >> 1) * HALF + ((am & 1) * 2 + m2) * 16) * D;
; #pragma unroll
;             for (int bj = 0; bj < 2; ++bj)
; #pragma unroll
;                 for (int n = 0; n < 2; ++n) *(f32x4*)(part + (po + bj * HALF + n * 16)) = gv[m2][bj][n] * acc[am >> 1][bj][(am & 1) * 2 + m2][n]; } }
;     __device__ __forceinline__ void operator()(const f32x4 (&acc)[2][2][4][2], const Unit& u, int wr, int wc, int fr, int fq) const {
;     ...
;         if (u.pm >= 32) { store_partials(acc, u, row0, col0, gate, part); return; }
.LBB0_1182:
	s_and_b64 vcc, exec, s[34:35]
	s_cbranch_vccz .LBB0_1184
	s_lshl_b32 s26, s91, 20
	v_add_u32_e32 v173, 0xffffe000, v190
	v_lshlrev_b32_e32 v173, 11, v173
	v_add3_u32 v172, v174, s26, v173
	s_mov_b64 s[30:31], s[12:13]
	v_add_u32_e32 v173, 0xffffe000, v190
	v_lshrrev_b32_e32 v173, 2, v173
	v_mad_u32_u24 v176, v173, s83, v174
	v_ashrrev_i32_e32 v177, 31, v176
	v_lshl_add_u64 v[176:177], v[176:177], 2, s[10:11]
	global_load_dwordx4 v[128:131], v[176:177], off
	global_load_dwordx4 v[132:135], v[176:177], off offset:64
	global_load_dwordx4 v[136:139], v[176:177], off offset:512
	global_load_dwordx4 v[140:143], v[176:177], off offset:576
	v_add_u32_e32 v173, 0xffffe010, v190
	v_lshrrev_b32_e32 v173, 2, v173
	v_mad_u32_u24 v176, v173, s83, v174
	v_ashrrev_i32_e32 v177, 31, v176
	v_lshl_add_u64 v[176:177], v[176:177], 2, s[10:11]
	global_load_dwordx4 v[144:147], v[176:177], off
	global_load_dwordx4 v[148:151], v[176:177], off offset:64
	global_load_dwordx4 v[152:155], v[176:177], off offset:512
	global_load_dwordx4 v[156:159], v[176:177], off offset:576
	v_ashrrev_i32_e32 v173, 31, v172
	v_lshl_add_u64 v[192:193], v[172:173], 2, s[12:13]
	s_waitcnt vmcnt(4)
	v_pk_mul_f32 v[124:125], v[124:125], v[128:129]
	v_pk_mul_f32 v[126:127], v[126:127], v[130:131]
	global_store_dwordx4 v[192:193], v[124:127], off
	v_pk_mul_f32 v[120:121], v[120:121], v[132:133]
	v_pk_mul_f32 v[122:123], v[122:123], v[134:135]
	global_store_dwordx4 v[192:193], v[120:123], off offset:64
	v_pk_mul_f32 v[108:109], v[108:109], v[136:137]
	v_pk_mul_f32 v[110:111], v[110:111], v[138:139]
	global_store_dwordx4 v[192:193], v[108:111], off offset:512
	v_pk_mul_f32 v[104:105], v[104:105], v[140:141]
	v_pk_mul_f32 v[106:107], v[106:107], v[142:143]
	global_store_dwordx4 v[192:193], v[104:107], off offset:576
	v_add_u32_e32 v173, 0xffffe020, v190
	v_lshrrev_b32_e32 v173, 2, v173
	v_mad_u32_u24 v176, v173, s83, v174
	v_ashrrev_i32_e32 v177, 31, v176
	v_lshl_add_u64 v[176:177], v[176:177], 2, s[10:11]
	global_load_dwordx4 v[128:131], v[176:177], off
	global_load_dwordx4 v[132:135], v[176:177], off offset:64
	global_load_dwordx4 v[136:139], v[176:177], off offset:512
	global_load_dwordx4 v[140:143], v[176:177], off offset:576
	s_waitcnt vmcnt(8)
	v_add_co_u32_e32 v194, vcc, 0x20000, v192
	s_nop 1
	v_addc_co_u32_e32 v195, vcc, 0, v193, vcc
	v_pk_mul_f32 v[116:117], v[116:117], v[144:145]
	v_pk_mul_f32 v[118:119], v[118:119], v[146:147]
	global_store_dwordx4 v[194:195], v[116:119], off
	v_pk_mul_f32 v[112:113], v[112:113], v[148:149]
	v_pk_mul_f32 v[114:115], v[114:115], v[150:151]
	global_store_dwordx4 v[194:195], v[112:115], off offset:64
	v_pk_mul_f32 v[100:101], v[100:101], v[152:153]
	v_pk_mul_f32 v[102:103], v[102:103], v[154:155]
	global_store_dwordx4 v[194:195], v[100:103], off offset:512
	v_pk_mul_f32 v[96:97], v[96:97], v[156:157]
	v_pk_mul_f32 v[98:99], v[98:99], v[158:159]
	global_store_dwordx4 v[194:195], v[96:99], off offset:576
	v_add_u32_e32 v173, 0xffffe030, v190
	v_lshrrev_b32_e32 v173, 2, v173
	v_mad_u32_u24 v176, v173, s83, v174
	v_ashrrev_i32_e32 v177, 31, v176
	v_lshl_add_u64 v[176:177], v[176:177], 2, s[10:11]
	global_load_dwordx4 v[144:147], v[176:177], off
	global_load_dwordx4 v[148:151], v[176:177], off offset:64
	global_load_dwordx4 v[152:155], v[176:177], off offset:512
	global_load_dwordx4 v[156:159], v[176:177], off offset:576
	s_waitcnt vmcnt(8)
	v_add_co_u32_e32 v194, vcc, 0x40000, v192
	s_nop 1
	v_addc_co_u32_e32 v195, vcc, 0, v193, vcc
	v_pk_mul_f32 v[92:93], v[92:93], v[128:129]
	v_pk_mul_f32 v[94:95], v[94:95], v[130:131]
	global_store_dwordx4 v[194:195], v[92:95], off
	v_pk_mul_f32 v[88:89], v[88:89], v[132:133]
	v_pk_mul_f32 v[90:91], v[90:91], v[134:135]
	global_store_dwordx4 v[194:195], v[88:91], off offset:64
	v_pk_mul_f32 v[76:77], v[76:77], v[136:137]
	v_pk_mul_f32 v[78:79], v[78:79], v[138:139]
	global_store_dwordx4 v[194:195], v[76:79], off offset:512
	v_pk_mul_f32 v[72:73], v[72:73], v[140:141]
	v_pk_mul_f32 v[74:75], v[74:75], v[142:143]
	global_store_dwordx4 v[194:195], v[72:75], off offset:576
	v_add_u32_e32 v173, 0xffffe080, v190
	v_lshrrev_b32_e32 v173, 2, v173
	v_mad_u32_u24 v176, v173, s83, v174
	v_ashrrev_i32_e32 v177, 31, v176
	v_lshl_add_u64 v[176:177], v[176:177], 2, s[10:11]
	global_load_dwordx4 v[128:131], v[176:177], off
	global_load_dwordx4 v[132:135], v[176:177], off offset:64
	global_load_dwordx4 v[136:139], v[176:177], off offset:512
	global_load_dwordx4 v[140:143], v[176:177], off offset:576
	s_waitcnt vmcnt(8)
; __device__ __forceinline__ void store_partials(const f32x4 (&acc)[2][2][4][2], const Unit& u, int row0, int col0, const float* gate, float* part) {
;     ...
;     for (int am = 0; am < 4; ++am) { f32x4 gv[2][2][2];
; #pragma unroll
;         for (int m2 = 0; m2 < 2; ++m2) { const int rr = row0 - SP + (am >> 1) * HALF + ((am & 1) * 2 + m2) * 16; const int go = (rr >> 2) * NMOD + col0;
; #pragma unroll
;             for (int bj = 0; bj < 2; ++bj)
; #pragma unroll
;                 for (int n = 0; n < 2; ++n) gv[m2][bj][n] = *(const f32x4*)(gate + (go + bj * HALF + n * 16)); }
; #pragma unroll
;         for (int m2 = 0; m2 < 2; ++m2) { const int po = poff + ((am >> 1) * HALF + ((am & 1) * 2 + m2) * 16) * D;
; #pragma unroll
;             for (int bj = 0; bj < 2; ++bj)
; #pragma unroll
;                 for (int n = 0; n < 2; ++n) *(f32x4*)(part + (po + bj * HALF + n * 16)) = gv[m2][bj][n] * acc[am >> 1][bj][(am & 1) * 2 + m2][n]; } }
	v_add_co_u32_e32 v194, vcc, 0x60000, v192
	s_nop 1
	v_addc_co_u32_e32 v195, vcc, 0, v193, vcc
	v_pk_mul_f32 v[84:85], v[84:85], v[144:145]
	v_pk_mul_f32 v[86:87], v[86:87], v[146:147]
	global_store_dwordx4 v[194:195], v[84:87], off
	v_pk_mul_f32 v[80:81], v[80:81], v[148:149]
	v_pk_mul_f32 v[82:83], v[82:83], v[150:151]
	global_store_dwordx4 v[194:195], v[80:83], off offset:64
	v_pk_mul_f32 v[68:69], v[68:69], v[152:153]
	v_pk_mul_f32 v[70:71], v[70:71], v[154:155]
	global_store_dwordx4 v[194:195], v[68:71], off offset:512
	v_pk_mul_f32 v[64:65], v[64:65], v[156:157]
	v_pk_mul_f32 v[66:67], v[66:67], v[158:159]
	global_store_dwordx4 v[194:195], v[64:67], off offset:576
	v_add_u32_e32 v173, 0xffffe090, v190
	v_lshrrev_b32_e32 v173, 2, v173
	v_mad_u32_u24 v176, v173, s83, v174
	v_ashrrev_i32_e32 v177, 31, v176
	v_lshl_add_u64 v[176:177], v[176:177], 2, s[10:11]
	global_load_dwordx4 v[144:147], v[176:177], off
	global_load_dwordx4 v[148:151], v[176:177], off offset:64
	global_load_dwordx4 v[152:155], v[176:177], off offset:512
	global_load_dwordx4 v[156:159], v[176:177], off offset:576
	s_waitcnt vmcnt(8)
	v_add_co_u32_e32 v194, vcc, 0x100000, v192
	s_nop 1
	v_addc_co_u32_e32 v195, vcc, 0, v193, vcc
	v_pk_mul_f32 v[60:61], v[60:61], v[128:129]
	v_pk_mul_f32 v[62:63], v[62:63], v[130:131]
	global_store_dwordx4 v[194:195], v[60:63], off
	v_pk_mul_f32 v[56:57], v[56:57], v[132:133]
	v_pk_mul_f32 v[58:59], v[58:59], v[134:135]
	global_store_dwordx4 v[194:195], v[56:59], off offset:64
	v_pk_mul_f32 v[44:45], v[44:45], v[136:137]
	v_pk_mul_f32 v[46:47], v[46:47], v[138:139]
	global_store_dwordx4 v[194:195], v[44:47], off offset:512
	v_pk_mul_f32 v[40:41], v[40:41], v[140:141]
	v_pk_mul_f32 v[42:43], v[42:43], v[142:143]
	global_store_dwordx4 v[194:195], v[40:43], off offset:576
	v_add_u32_e32 v173, 0xffffe0a0, v190
	v_lshrrev_b32_e32 v173, 2, v173
	v_mad_u32_u24 v176, v173, s83, v174
	v_ashrrev_i32_e32 v177, 31, v176
	v_lshl_add_u64 v[176:177], v[176:177], 2, s[10:11]
	global_load_dwordx4 v[128:131], v[176:177], off
	global_load_dwordx4 v[132:135], v[176:177], off offset:64
	global_load_dwordx4 v[136:139], v[176:177], off offset:512
	global_load_dwordx4 v[140:143], v[176:177], off offset:576
	s_waitcnt vmcnt(8)
	v_add_co_u32_e32 v194, vcc, 0x120000, v192
	s_nop 1
	v_addc_co_u32_e32 v195, vcc, 0, v193, vcc
	v_pk_mul_f32 v[52:53], v[52:53], v[144:145]
	v_pk_mul_f32 v[54:55], v[54:55], v[146:147]
	global_store_dwordx4 v[194:195], v[52:55], off
	v_pk_mul_f32 v[48:49], v[48:49], v[148:149]
	v_pk_mul_f32 v[50:51], v[50:51], v[150:151]
	global_store_dwordx4 v[194:195], v[48:51], off offset:64
	v_pk_mul_f32 v[36:37], v[36:37], v[152:153]
	v_pk_mul_f32 v[38:39], v[38:39], v[154:155]
	global_store_dwordx4 v[194:195], v[36:39], off offset:512
	v_pk_mul_f32 v[32:33], v[32:33], v[156:157]
	v_pk_mul_f32 v[34:35], v[34:35], v[158:159]
	global_store_dwordx4 v[194:195], v[32:35], off offset:576
	v_add_u32_e32 v173, 0xffffe0b0, v190
	v_lshrrev_b32_e32 v173, 2, v173
	v_mad_u32_u24 v176, v173, s83, v174
	v_ashrrev_i32_e32 v177, 31, v176
	v_lshl_add_u64 v[176:177], v[176:177], 2, s[10:11]
	global_load_dwordx4 v[144:147], v[176:177], off
	global_load_dwordx4 v[148:151], v[176:177], off offset:64
	global_load_dwordx4 v[152:155], v[176:177], off offset:512
	global_load_dwordx4 v[156:159], v[176:177], off offset:576
	s_waitcnt vmcnt(8)
	v_add_co_u32_e32 v194, vcc, 0x140000, v192
	s_nop 1
	v_addc_co_u32_e32 v195, vcc, 0, v193, vcc
	v_pk_mul_f32 v[28:29], v[28:29], v[128:129]
	v_pk_mul_f32 v[30:31], v[30:31], v[130:131]
	global_store_dwordx4 v[194:195], v[28:31], off
	v_pk_mul_f32 v[24:25], v[24:25], v[132:133]
	v_pk_mul_f32 v[26:27], v[26:27], v[134:135]
	global_store_dwordx4 v[194:195], v[24:27], off offset:64
	v_pk_mul_f32 v[12:13], v[12:13], v[136:137]
	v_pk_mul_f32 v[14:15], v[14:15], v[138:139]
	global_store_dwordx4 v[194:195], v[12:15], off offset:512
	v_pk_mul_f32 v[8:9], v[8:9], v[140:141]
	v_pk_mul_f32 v[10:11], v[10:11], v[142:143]
	global_store_dwordx4 v[194:195], v[8:11], off offset:576
	s_waitcnt vmcnt(4)
	v_add_co_u32_e32 v194, vcc, 0x160000, v192
	s_nop 1
	v_addc_co_u32_e32 v195, vcc, 0, v193, vcc
	v_pk_mul_f32 v[20:21], v[20:21], v[144:145]
	v_pk_mul_f32 v[22:23], v[22:23], v[146:147]
	global_store_dwordx4 v[194:195], v[20:23], off
	v_pk_mul_f32 v[16:17], v[16:17], v[148:149]
	v_pk_mul_f32 v[18:19], v[18:19], v[150:151]
	global_store_dwordx4 v[194:195], v[16:19], off offset:64
	v_pk_mul_f32 v[4:5], v[4:5], v[152:153]
	v_pk_mul_f32 v[6:7], v[6:7], v[154:155]
	global_store_dwordx4 v[194:195], v[4:7], off offset:512
	v_pk_mul_f32 v[128:129], v[0:1], v[156:157]
	v_pk_mul_f32 v[130:131], v[2:3], v[158:159]
